# v57: grid barrier XCD leaders poll the monotonic TOP counter directly instead of waiting for the TOPGEN bump
# baseline (speedup 1.0000x reference)
.LBB0_128:
	s_or_b64 exec, exec, s[8:9]
	v_cvt_f32_u32_e32 v4, v1
	s_waitcnt vmcnt(0)
	v_readfirstlane_b32 s6, v3
	s_add_u32 s8, s82, 0x7500
	s_addc_u32 s9, s83, 0
	v_rcp_iflag_f32_e32 v4, v4
	v_add_u32_e32 v2, s6, v2
	v_add_u32_e32 v5, 1, v2
	s_mov_b64 s[10:11], -1
	v_mul_f32_e32 v3, 0x4f7ffffe, v4
	v_cvt_u32_f32_e32 v3, v3
	v_sub_u32_e32 v4, 0, v1
	v_mul_lo_u32 v4, v4, v3
	v_mul_hi_u32 v4, v3, v4
	v_add_u32_e32 v3, v3, v4
	v_mul_hi_u32 v3, v2, v3
	v_mul_lo_u32 v4, v3, v1
	v_sub_u32_e32 v2, v2, v4
	v_add_u32_e32 v6, 1, v3
	v_cmp_ge_u32_e32 vcc, v2, v1
	v_sub_u32_e32 v4, v2, v1
	s_nop 0
	v_cndmask_b32_e32 v3, v3, v6, vcc
	v_cndmask_b32_e32 v2, v2, v4, vcc
	v_add_u32_e32 v4, 1, v3
	v_cmp_ge_u32_e32 vcc, v2, v1
	s_nop 1
	v_cndmask_b32_e32 v4, v3, v4, vcc
	v_mul_lo_u32 v2, v1, v4
	v_add_u32_e32 v1, v2, v1
	v_mov_b32_e32 v253, v1
	v_mov_b32_e32 v252, 0x7000
	v_cmp_ne_u32_e32 vcc, v5, v1
	v_mov_b64_e32 v[2:3], s[8:9]
	s_and_saveexec_b64 s[6:7], vcc
	s_cbranch_execz .LBB0_140
	v_mov_b32_e32 v1, 0
	global_load_dword v2, v252, s[82:83] offset:1024 sc1
	s_mov_b64 s[14:15], 0
	s_waitcnt vmcnt(0)
	v_cmp_lt_u32_e32 vcc, v2, v253
	s_and_saveexec_b64 s[12:13], vcc
	s_cbranch_execz .LBB0_139
	s_add_u32 s10, s82, 0x4200
	s_addc_u32 s11, s83, 0
	s_mov_b32 s24, 1
	s_branch .LBB0_132

.LBB0_134:
	global_load_dword v2, v252, s[82:83] offset:1024 sc1
	s_add_i32 s24, s24, 1
	s_mov_b64 s[18:19], -1
	s_waitcnt vmcnt(0)
	v_cmp_ge_u32_e32 vcc, v2, v253
	s_orn2_b64 s[22:23], vcc, exec
	s_branch .LBB0_131

.LBB0_611:
	s_or_b64 exec, exec, s[6:7]
	v_cvt_f32_u32_e32 v4, v1
	s_waitcnt vmcnt(0)
	v_readfirstlane_b32 s4, v3
	s_add_u32 s6, s82, 0x7500
	s_addc_u32 s7, s83, 0
	v_rcp_iflag_f32_e32 v4, v4
	v_add_u32_e32 v2, s4, v2
	v_add_u32_e32 v5, 1, v2
	s_mov_b64 s[8:9], -1
	v_mul_f32_e32 v3, 0x4f7ffffe, v4
	v_cvt_u32_f32_e32 v3, v3
	v_sub_u32_e32 v4, 0, v1
	v_mul_lo_u32 v4, v4, v3
	v_mul_hi_u32 v4, v3, v4
	v_add_u32_e32 v3, v3, v4
	v_mul_hi_u32 v3, v2, v3
	v_mul_lo_u32 v4, v3, v1
	v_sub_u32_e32 v2, v2, v4
	v_add_u32_e32 v6, 1, v3
	v_cmp_ge_u32_e32 vcc, v2, v1
	v_sub_u32_e32 v4, v2, v1
	s_nop 0
	v_cndmask_b32_e32 v3, v3, v6, vcc
	v_cndmask_b32_e32 v2, v2, v4, vcc
	v_add_u32_e32 v4, 1, v3
	v_cmp_ge_u32_e32 vcc, v2, v1
	s_nop 1
	v_cndmask_b32_e32 v4, v3, v4, vcc
	v_mul_lo_u32 v2, v1, v4
	v_add_u32_e32 v1, v2, v1
	v_mov_b32_e32 v253, v1
	v_mov_b32_e32 v252, 0x7000
	v_cmp_ne_u32_e32 vcc, v5, v1
	v_mov_b64_e32 v[2:3], s[6:7]
	s_and_saveexec_b64 s[4:5], vcc
	s_cbranch_execz .LBB0_623
	v_mov_b32_e32 v1, 0
	global_load_dword v2, v252, s[82:83] offset:1024 sc1
	s_mov_b64 s[12:13], 0
	s_waitcnt vmcnt(0)
	v_cmp_lt_u32_e32 vcc, v2, v253
	s_and_saveexec_b64 s[10:11], vcc
	s_cbranch_execz .LBB0_622
	s_add_u32 s8, s82, 0x4200
	s_addc_u32 s9, s83, 0
	s_mov_b32 s24, 1
	s_branch .LBB0_615

.LBB0_1248:
	s_or_b64 exec, exec, s[6:7]
	v_cvt_f32_u32_e32 v4, v1
	s_waitcnt vmcnt(0)
	v_readfirstlane_b32 s4, v3
	s_add_u32 s6, s82, 0x7500
	s_addc_u32 s7, s83, 0
	v_rcp_iflag_f32_e32 v4, v4
	v_add_u32_e32 v2, s4, v2
	v_add_u32_e32 v5, 1, v2
	s_mov_b64 s[8:9], -1
	v_mul_f32_e32 v3, 0x4f7ffffe, v4
	v_cvt_u32_f32_e32 v3, v3
	v_sub_u32_e32 v4, 0, v1
	v_mul_lo_u32 v4, v4, v3
	v_mul_hi_u32 v4, v3, v4
	v_add_u32_e32 v3, v3, v4
	v_mul_hi_u32 v3, v2, v3
	v_mul_lo_u32 v4, v3, v1
	v_sub_u32_e32 v2, v2, v4
	v_add_u32_e32 v6, 1, v3
	v_cmp_ge_u32_e32 vcc, v2, v1
	v_sub_u32_e32 v4, v2, v1
	s_nop 0
	v_cndmask_b32_e32 v3, v3, v6, vcc
	v_cndmask_b32_e32 v2, v2, v4, vcc
	v_add_u32_e32 v4, 1, v3
	v_cmp_ge_u32_e32 vcc, v2, v1
	s_nop 1
	v_cndmask_b32_e32 v4, v3, v4, vcc
	v_mul_lo_u32 v2, v1, v4
	v_add_u32_e32 v1, v2, v1
	v_mov_b32_e32 v253, v1
	v_mov_b32_e32 v252, 0x7000
	v_cmp_ne_u32_e32 vcc, v5, v1
	v_mov_b64_e32 v[2:3], s[6:7]
	s_and_saveexec_b64 s[4:5], vcc
	s_cbranch_execz .LBB0_1260
	v_mov_b32_e32 v1, 0
	global_load_dword v2, v252, s[82:83] offset:1024 sc1
	s_mov_b64 s[12:13], 0
	s_waitcnt vmcnt(0)
	v_cmp_lt_u32_e32 vcc, v2, v253
	s_and_saveexec_b64 s[10:11], vcc
	s_cbranch_execz .LBB0_1259
	s_add_u32 s8, s82, 0x4200
	s_addc_u32 s9, s83, 0
	s_mov_b32 s22, 1
	s_branch .LBB0_1252

.LBB0_1254:
	global_load_dword v2, v252, s[82:83] offset:1024 sc1
	s_add_i32 s22, s22, 1
	s_mov_b64 s[16:17], -1
	s_waitcnt vmcnt(0)
	v_cmp_ge_u32_e32 vcc, v2, v253
	s_orn2_b64 s[20:21], vcc, exec
	s_branch .LBB0_1251

.LBB0_1872:
	s_or_b64 exec, exec, s[6:7]
	v_cvt_f32_u32_e32 v4, v1
	s_waitcnt vmcnt(0)
	v_readfirstlane_b32 s4, v3
	s_add_u32 s6, s82, 0x7500
	s_addc_u32 s7, s83, 0
	v_rcp_iflag_f32_e32 v4, v4
	v_add_u32_e32 v2, s4, v2
	v_add_u32_e32 v5, 1, v2
	s_mov_b64 s[8:9], -1
	v_mul_f32_e32 v3, 0x4f7ffffe, v4
	v_cvt_u32_f32_e32 v3, v3
	v_sub_u32_e32 v4, 0, v1
	v_mul_lo_u32 v4, v4, v3
	v_mul_hi_u32 v4, v3, v4
	v_add_u32_e32 v3, v3, v4
	v_mul_hi_u32 v3, v2, v3
	v_mul_lo_u32 v4, v3, v1
	v_sub_u32_e32 v2, v2, v4
	v_add_u32_e32 v6, 1, v3
	v_cmp_ge_u32_e32 vcc, v2, v1
	v_sub_u32_e32 v4, v2, v1
	s_nop 0
	v_cndmask_b32_e32 v3, v3, v6, vcc
	v_cndmask_b32_e32 v2, v2, v4, vcc
	v_add_u32_e32 v4, 1, v3
	v_cmp_ge_u32_e32 vcc, v2, v1
	s_nop 1
	v_cndmask_b32_e32 v4, v3, v4, vcc
	v_mul_lo_u32 v2, v1, v4
	v_add_u32_e32 v1, v2, v1
	v_mov_b32_e32 v253, v1
	v_mov_b32_e32 v252, 0x7000
	v_cmp_ne_u32_e32 vcc, v5, v1
	v_mov_b64_e32 v[2:3], s[6:7]
	s_and_saveexec_b64 s[4:5], vcc
	s_cbranch_execz .LBB0_1884
	v_mov_b32_e32 v1, 0
	global_load_dword v2, v252, s[82:83] offset:1024 sc1
	s_mov_b64 s[14:15], 0
	s_waitcnt vmcnt(0)
	v_cmp_lt_u32_e32 vcc, v2, v253
	s_and_saveexec_b64 s[12:13], vcc
	s_cbranch_execz .LBB0_1883
	s_add_u32 s8, s82, 0x4200
	s_addc_u32 s9, s83, 0
	s_mov_b32 s24, 1
	s_branch .LBB0_1876
